# scan pass 2 state-chaining step on the f32-operand matrix core (v_mfma_f32_16x16x4_f32, f32 in / f32 accumulate) instead of per-thread f32 VALU fma rows
# speedup vs baseline: 1.0002x; 1.0002x over previous
; #define LAS __attribute__((address_space(3)))
; __device__ __forceinline__ void scan_pass2(const ScanP& sp, int b, int h, int seg, LAS unsigned char* lds) {
;     ...
;     const int j = tid >> 3, i8 = (tid & 7) * 8;
;     *(LAS f32x4*)(Hc + j * 64 + i8) = (f32x4){0.f, 0.f, 0.f, 0.f}; *(LAS f32x4*)(Hc + j * 64 + i8 + 4) = (f32x4){0.f, 0.f, 0.f, 0.f};
;     __syncthreads();
;     for (int s = 0; s < seg; ++s) {
;         const float* HE = sp.HE + (size_t)((b * 8 + h) * 4 + s) * 4096; const float* PE = sp.PE + (size_t)((b * 8 + h) * 4 + s) * 4096;
;         f32x4 a0 = *(const f32x4*)(HE + j * 64 + i8), a1 = *(const f32x4*)(HE + j * 64 + i8 + 4);
;         f32x4 pvr[16];
; #pragma unroll
;         for (int jq = 0; jq < 16; ++jq) pvr[jq] = *(const f32x4*)(PE + j * 64 + 4 * jq);
; #pragma unroll
;         for (int jq = 0; jq < 16; ++jq) {
; #pragma unroll
;             for (int q = 0; q < 4; ++q) {
;                 const f32x4 h0 = *(const LAS f32x4*)(Hc + (4 * jq + q) * 64 + i8), h1 = *(const LAS f32x4*)(Hc + (4 * jq + q) * 64 + i8 + 4);
;                 a0 += h0 * pvr[jq][q]; a1 += h1 * pvr[jq][q];
;             }
;         }
;         *(LAS f32x4*)(Hn + j * 64 + i8) = a0; *(LAS f32x4*)(Hn + j * 64 + i8 + 4) = a1;
;         __syncthreads();
;         LAS float* t_ = Hc; Hc = Hn; Hn = t_;
;     }
.LBB0_336:
	s_or_b64 exec, exec, s[0:1]
	v_lshlrev_b32_e32 v0, 3, v34
	v_ashrrev_i32_e32 v35, 3, v34
	v_and_b32_e32 v36, 56, v0
	s_mov_b32 s92, s93
	s_and_b32 s0, s3, 3
	v_lshlrev_b32_e32 v0, 8, v35
	v_lshlrev_b32_e32 v37, 2, v36
	s_mov_b32 s94, s93
	s_mov_b32 s95, s93
	v_mov_b64_e32 v[2:3], s[92:93]
	v_lshlrev_b32_e32 v30, 6, v35
	s_mov_b32 s7, 0
	v_add3_u32 v0, 0, v0, v37
	v_mov_b64_e32 v[4:5], s[94:95]
	s_cmp_eq_u32 s0, 0
	ds_write_b128 v0, v[2:5]
	ds_write_b128 v0, v[2:5] offset:16
	s_waitcnt lgkmcnt(0)
	s_barrier
	s_cbranch_scc1 .LBB0_339
	s_and_b32 s1, s3, 0xffffffe0
	s_lshl_b32 s5, s2, 2
	s_or_b32 s6, s5, s1
	s_ashr_i32 s7, s6, 31
	s_lshl_b64 s[6:7], s[6:7], 14
	s_add_u32 s6, s16, s6
	v_ashrrev_i32_e32 v31, 31, v30
	s_addc_u32 s7, s17, s7
	v_and_b32_e32 v116, 63, v34
	v_and_b32_e32 v120, 15, v116
	v_lshrrev_b32_e32 v121, 4, v116
	s_lshr_b32 s8, s4, 6
	s_lshr_b32 s9, s8, 1
	s_and_b32 s8, s8, 1
	s_lshl_b32 s9, s9, 12
	s_lshl_b32 s8, s8, 7
	v_lshlrev_b32_e32 v116, 8, v120
	v_lshl_add_u32 v116, v121, 6, v116
	v_add_u32_e32 v116, s9, v116
	v_add_u32_e32 v116, 0x400000, v116
	v_mov_b32_e32 v117, 0
	v_lshlrev_b32_e32 v127, 10, v121
	v_lshl_add_u32 v127, v120, 2, v127
	v_add_u32_e32 v127, s9, v127
	v_add_u32_e32 v127, s8, v127
	v_mov_b32_e32 v118, v127
	v_mov_b32_e32 v119, 0
	v_lshlrev_b32_e32 v126, 12, v121
	v_lshl_add_u32 v126, v120, 2, v126
	v_add_u32_e32 v126, s8, v126
	v_lshl_add_u64 v[122:123], s[6:7], 0, v[116:117]
	v_lshl_add_u64 v[124:125], s[6:7], 0, v[118:119]
	v_and_b32_e32 v0, 7, v34
	v_lshl_add_u64 v[32:33], v[30:31], 2, s[6:7]
	s_mov_b32 s7, 0
	s_add_i32 s5, 0, 0x4000
	v_lshlrev_b32_e32 v0, 5, v0
	s_mov_b32 s1, s0
.LBB0_338:
	s_mov_b32 s6, s7
	global_load_dwordx4 v[46:49], v[122:123], off
	global_load_dwordx4 v[50:53], v[122:123], off offset:16
	global_load_dwordx4 v[54:57], v[122:123], off offset:32
	global_load_dwordx4 v[58:61], v[122:123], off offset:48
	global_load_dword v62, v[124:125], off
	global_load_dword v63, v[124:125], off offset:256
	global_load_dword v64, v[124:125], off offset:512
	global_load_dword v65, v[124:125], off offset:768
	global_load_dword v66, v[124:125], off offset:64
	global_load_dword v67, v[124:125], off offset:320
	global_load_dword v68, v[124:125], off offset:576
	global_load_dword v69, v[124:125], off offset:832
	v_add_u32_e32 v31, s6, v126
	ds_read_b32 v70, v31
	ds_read_b32 v106, v31 offset:64
	ds_read_b32 v71, v31 offset:256
	ds_read_b32 v107, v31 offset:320
	ds_read_b32 v72, v31 offset:512
	ds_read_b32 v108, v31 offset:576
	ds_read_b32 v73, v31 offset:768
	ds_read_b32 v109, v31 offset:832
	ds_read_b32 v74, v31 offset:1024
	ds_read_b32 v110, v31 offset:1088
	ds_read_b32 v75, v31 offset:1280
	ds_read_b32 v111, v31 offset:1344
	ds_read_b32 v76, v31 offset:1536
	ds_read_b32 v112, v31 offset:1600
	s_mov_b32 s7, s5
	s_add_i32 s1, s1, -1
	s_mov_b64 s[8:9], 0x4000
	v_lshl_add_u64 v[32:33], v[32:33], 0, s[8:9]
	v_lshl_add_u64 v[122:123], v[122:123], 0, s[8:9]
	v_lshl_add_u64 v[124:125], v[124:125], 0, s[8:9]
	s_cmp_eq_u32 s1, 0
	s_mov_b32 s5, s6
	s_waitcnt vmcnt(0)
	s_waitcnt lgkmcnt(13)
	v_mfma_f32_16x16x4_f32 v[62:65], v46, v70, v[62:65]
	s_waitcnt lgkmcnt(12)
	v_mfma_f32_16x16x4_f32 v[66:69], v46, v106, v[66:69]
	ds_read_b32 v77, v31 offset:1792
	ds_read_b32 v113, v31 offset:1856
	s_waitcnt lgkmcnt(13)
	v_mfma_f32_16x16x4_f32 v[62:65], v47, v71, v[62:65]
	s_waitcnt lgkmcnt(12)
	v_mfma_f32_16x16x4_f32 v[66:69], v47, v107, v[66:69]
	ds_read_b32 v78, v31 offset:2048
	ds_read_b32 v114, v31 offset:2112
	s_waitcnt lgkmcnt(13)
	v_mfma_f32_16x16x4_f32 v[62:65], v48, v72, v[62:65]
	s_waitcnt lgkmcnt(12)
	v_mfma_f32_16x16x4_f32 v[66:69], v48, v108, v[66:69]
	ds_read_b32 v79, v31 offset:2304
	ds_read_b32 v115, v31 offset:2368
	s_waitcnt lgkmcnt(13)
	v_mfma_f32_16x16x4_f32 v[62:65], v49, v73, v[62:65]
	s_waitcnt lgkmcnt(12)
	v_mfma_f32_16x16x4_f32 v[66:69], v49, v109, v[66:69]
	ds_read_b32 v80, v31 offset:2560
	ds_read_b32 v116, v31 offset:2624
	s_waitcnt lgkmcnt(13)
	v_mfma_f32_16x16x4_f32 v[62:65], v50, v74, v[62:65]
	s_waitcnt lgkmcnt(12)
	v_mfma_f32_16x16x4_f32 v[66:69], v50, v110, v[66:69]
	ds_read_b32 v81, v31 offset:2816
	ds_read_b32 v117, v31 offset:2880
	s_waitcnt lgkmcnt(13)
	v_mfma_f32_16x16x4_f32 v[62:65], v51, v75, v[62:65]
	s_waitcnt lgkmcnt(12)
	v_mfma_f32_16x16x4_f32 v[66:69], v51, v111, v[66:69]
	ds_read_b32 v82, v31 offset:3072
	ds_read_b32 v118, v31 offset:3136
	s_waitcnt lgkmcnt(13)
	v_mfma_f32_16x16x4_f32 v[62:65], v52, v76, v[62:65]
	s_waitcnt lgkmcnt(12)
	v_mfma_f32_16x16x4_f32 v[66:69], v52, v112, v[66:69]
	ds_read_b32 v83, v31 offset:3328
	ds_read_b32 v119, v31 offset:3392
	s_waitcnt lgkmcnt(13)
	v_mfma_f32_16x16x4_f32 v[62:65], v53, v77, v[62:65]
	s_waitcnt lgkmcnt(12)
	v_mfma_f32_16x16x4_f32 v[66:69], v53, v113, v[66:69]
	ds_read_b32 v84, v31 offset:3584
	ds_read_b32 v120, v31 offset:3648
	s_waitcnt lgkmcnt(13)
	v_mfma_f32_16x16x4_f32 v[62:65], v54, v78, v[62:65]
	s_waitcnt lgkmcnt(12)
	v_mfma_f32_16x16x4_f32 v[66:69], v54, v114, v[66:69]
	ds_read_b32 v85, v31 offset:3840
	ds_read_b32 v121, v31 offset:3904
	s_waitcnt lgkmcnt(13)
	v_mfma_f32_16x16x4_f32 v[62:65], v55, v79, v[62:65]
	s_waitcnt lgkmcnt(12)
	v_mfma_f32_16x16x4_f32 v[66:69], v55, v115, v[66:69]
	s_waitcnt lgkmcnt(11)
	v_mfma_f32_16x16x4_f32 v[62:65], v56, v80, v[62:65]
	s_waitcnt lgkmcnt(10)
	v_mfma_f32_16x16x4_f32 v[66:69], v56, v116, v[66:69]
	s_waitcnt lgkmcnt(9)
	v_mfma_f32_16x16x4_f32 v[62:65], v57, v81, v[62:65]
	s_waitcnt lgkmcnt(8)
	v_mfma_f32_16x16x4_f32 v[66:69], v57, v117, v[66:69]
	s_waitcnt lgkmcnt(7)
	v_mfma_f32_16x16x4_f32 v[62:65], v58, v82, v[62:65]
	s_waitcnt lgkmcnt(6)
	v_mfma_f32_16x16x4_f32 v[66:69], v58, v118, v[66:69]
	s_waitcnt lgkmcnt(5)
	v_mfma_f32_16x16x4_f32 v[62:65], v59, v83, v[62:65]
	s_waitcnt lgkmcnt(4)
	v_mfma_f32_16x16x4_f32 v[66:69], v59, v119, v[66:69]
	s_waitcnt lgkmcnt(3)
	v_mfma_f32_16x16x4_f32 v[62:65], v60, v84, v[62:65]
	s_waitcnt lgkmcnt(2)
	v_mfma_f32_16x16x4_f32 v[66:69], v60, v120, v[66:69]
	s_waitcnt lgkmcnt(1)
	v_mfma_f32_16x16x4_f32 v[62:65], v61, v85, v[62:65]
	s_waitcnt lgkmcnt(0)
	v_mfma_f32_16x16x4_f32 v[66:69], v61, v121, v[66:69]
	s_nop 15
	s_nop 3
	v_add_u32_e32 v10, s7, v127
	ds_write_b32 v10, v62
	ds_write_b32 v10, v63 offset:256
	ds_write_b32 v10, v64 offset:512
	ds_write_b32 v10, v65 offset:768
	ds_write_b32 v10, v66 offset:64
	ds_write_b32 v10, v67 offset:320
	ds_write_b32 v10, v68 offset:576
	ds_write_b32 v10, v69 offset:832
	s_waitcnt lgkmcnt(0)
	s_barrier
	s_cbranch_scc0 .LBB0_338
